# QUP/KVUP tiles moved off the 32 CUs that run the compression-MLP GEMMs (they take no q/kv up-projection tile; 32 other CUs take two)
# baseline (speedup 1.0000x reference)
;     __host__ __device__ bool next(int i, Unit& u) const {
;         const long L = (long)i * G + c; if (L >= nwg) return false;
;         int wgid = (int)L; { const int q = nwg / NXCD, r = nwg % NXCD, xcd = wgid % NXCD, off = wgid / NXCD; wgid = (xcd < r ? xcd * (q + 1) : r * (q + 1) + (xcd - r) * q) + off; }
;         const int nig = WGM * nN, gid = wgid / nig, fm = gid * WGM, gsz = (nM - fm) < WGM ? (nM - fm) : WGM;
;         u.pm = fm + ((wgid % nig) % gsz); u.pn = (wgid % nig) / gsz; return true;
;     }
; template <class Epi, class Sched, bool ALIGN_EPI = false, bool SP2 = false>
; __device__ __forceinline__ void gemm_phase(PG8_LAS unsigned char* lds, const Gemm g, const Sched& S, const Epi& E, const int wave0) {
;     ...
;     if (!S.next(0, cur)) return;
.LBB0_1244:
	s_and_b64 vcc, exec, s[44:45]
	s_cbranch_vccz .LBB0_1647
	s_cmpk_gt_i32 s22, 0xff
	s_mov_b64 s[4:5], -1
	s_cbranch_scc0 .LBB0_1645
	s_cmpk_eq_i32 s22, 0x100
	s_mov_b64 s[2:3], -1
	s_cbranch_scc0 .LBB0_1644
	s_min_u32 s2, s72, 0xe0
	s_cmp_ge_u32 s21, s2
	s_cselect_b32 s21, 0x7fffff, s21
	s_cmp_lt_i32 s21, s42
	v_mov_b32_e32 v0, v246
	s_cselect_b64 s[2:3], -1, 0
	s_cmp_ge_i32 s21, s42
	s_cbranch_scc1 .LBB0_1249
	s_lshl_b32 s7, s20, 3
	v_cvt_f32_u32_e32 v1, s7
	s_ashr_i32 s5, s21, 31
	s_lshr_b32 s5, s5, 29
	s_add_i32 s5, s21, s5
	v_rcp_iflag_f32_e32 v1, v1
	s_ashr_i32 s6, s5, 3
	s_and_b32 s5, s5, -8
	s_sub_i32 s5, s21, s5
	v_mul_f32_e32 v1, 0x4f7ffffe, v1
	v_cvt_u32_f32_e32 v1, v1
	s_lshr_b32 s4, s42, 3
	s_lshr_b32 s8, s5, 31
	s_or_b32 s4, s4, s8
	s_sub_i32 s8, 0, s7
	v_readfirstlane_b32 s9, v1
	s_mul_i32 s4, s5, s4
	s_mul_i32 s8, s8, s9
	s_add_i32 s4, s4, s6
	s_mul_hi_u32 s8, s9, s8
	s_abs_i32 s6, s4
	s_add_i32 s9, s9, s8
	s_mul_hi_u32 s8, s6, s9
	s_mul_i32 s9, s8, s7
	s_sub_i32 s6, s6, s9
	s_ashr_i32 s5, s4, 31
	s_add_i32 s9, s8, 1
	s_sub_i32 s10, s6, s7
	s_cmp_ge_u32 s6, s7
	s_cselect_b32 s8, s9, s8
	s_cselect_b32 s6, s10, s6
	s_add_i32 s9, s8, 1
	s_cmp_ge_u32 s6, s7
	s_cselect_b32 s6, s9, s8
	s_xor_b32 s6, s6, s5
	s_sub_i32 s5, s6, s5
	s_lshl_b32 s6, s5, 3
	s_sub_i32 s8, s35, s6
	s_min_i32 s8, s8, 8
	s_mul_i32 s5, s5, s7
	s_sext_i32_i16 s7, s8
	v_cvt_f32_i32_e32 v1, s7
	s_sub_i32 s9, s4, s5
	s_sext_i32_i16 s4, s9
	v_cvt_f32_i32_e32 v2, s4
	v_rcp_iflag_f32_e32 v3, v1
	s_xor_b32 s4, s4, s7
	s_ashr_i32 s4, s4, 30
	s_or_b32 s7, s4, 1
	v_mul_f32_e32 v3, v2, v3
	v_trunc_f32_e32 v3, v3
	v_fma_f32 v2, -v3, v1, v2
	v_cvt_i32_f32_e32 v3, v3
	v_cmp_ge_f32_e64 s[4:5], |v2|, |v1|
	s_and_b64 s[4:5], s[4:5], exec
	s_cselect_b32 s4, s7, 0
	v_readfirstlane_b32 s5, v3
	s_add_i32 s4, s5, s4
	s_sext_i32_i16 s52, s4
	s_mul_i32 s4, s4, s8
	s_sub_i32 s4, s9, s4
	s_sext_i32_i16 s4, s4
	s_add_i32 s8, s6, s4

;     __host__ __device__ bool next(int i, Unit& u) const {
;         const long L = (long)i * G + c; if (L >= nwg) return false;
;         int wgid = (int)L; { const int q = nwg / NXCD, r = nwg % NXCD, xcd = wgid % NXCD, off = wgid / NXCD; wgid = (xcd < r ? xcd * (q + 1) : r * (q + 1) + (xcd - r) * q) + off; }
;         const int nig = WGM * nN, gid = wgid / nig, fm = gid * WGM, gsz = (nM - fm) < WGM ? (nM - fm) : WGM;
;         u.pm = fm + ((wgid % nig) % gsz); u.pn = (wgid % nig) / gsz; return true;
; template <class Epi, class Sched, bool ALIGN_EPI = false, bool SP2 = false>
; __device__ __forceinline__ void gemm_phase(PG8_LAS unsigned char* lds, const Gemm g, const Sched& S, const Epi& E, const int wave0) {
;     ...
;         const bool has_next = S.next(ui + 1, nxt);
.LBB0_1255:
	s_add_i32 s25, s25, 1
	s_min_u32 s6, s72, 0xe0
	s_mul_hi_u32 s7, s25, s6
	s_mul_i32 s6, s25, s6
	s_add_u32 s48, s6, s21
	s_addc_u32 s49, s7, s26
	v_mov_b64_e32 v[0:1], s[42:43]
	v_cmp_ge_i64_e32 vcc, s[48:49], v[0:1]
	v_cmp_lt_i64_e64 s[6:7], s[48:49], v[0:1]
	s_cbranch_vccnz .LBB0_1257
	s_ashr_i32 s9, s48, 31
	s_lshr_b32 s9, s9, 29
	s_add_i32 s9, s48, s9
	s_ashr_i32 s17, s9, 3
	s_and_b32 s9, s9, -8
	s_sub_i32 s9, s48, s9
	s_lshr_b32 s18, s9, 31
	s_or_b32 s18, s27, s18
	s_mul_i32 s9, s18, s9
	s_add_i32 s9, s9, s17
	s_abs_i32 s18, s9
	s_mul_hi_u32 s19, s18, s16
	s_mul_i32 s44, s19, s85
	s_sub_i32 s18, s18, s44
	s_ashr_i32 s17, s9, 31
	s_add_i32 s44, s19, 1
	s_sub_i32 s45, s18, s85
	s_cmp_ge_u32 s18, s85
	s_cselect_b32 s19, s44, s19
	s_cselect_b32 s18, s45, s18
	s_add_i32 s44, s19, 1
	s_cmp_ge_u32 s18, s85
	s_cselect_b32 s18, s44, s19
	s_xor_b32 s18, s18, s17
	s_sub_i32 s17, s18, s17
	s_lshl_b32 s18, s17, 3
	s_sub_i32 s19, s35, s18
	s_min_i32 s19, s19, 8
	s_abs_i32 s44, s19
	v_cvt_f32_u32_e32 v0, s44
	s_sub_i32 s46, 0, s44
	s_mul_i32 s17, s17, s85
	s_sub_i32 s9, s9, s17
	v_rcp_iflag_f32_e32 v0, v0
	s_abs_i32 s45, s9
	s_xor_b32 s17, s9, s19
	s_ashr_i32 s17, s17, 31
	v_mul_f32_e32 v0, 0x4f7ffffe, v0
	v_cvt_u32_f32_e32 v0, v0
	s_nop 0
	v_readfirstlane_b32 s47, v0
	s_mul_i32 s46, s46, s47
	s_mul_hi_u32 s46, s47, s46
	s_add_i32 s47, s47, s46
	s_mul_hi_u32 s46, s45, s47
	s_mul_i32 s47, s46, s44
	s_sub_i32 s45, s45, s47
	s_add_i32 s47, s46, 1
	s_sub_i32 s48, s45, s44
	s_cmp_ge_u32 s45, s44
	s_cselect_b32 s46, s47, s46
	s_cselect_b32 s45, s48, s45
	s_add_i32 s47, s46, 1
	s_cmp_ge_u32 s45, s44
	s_cselect_b32 s44, s47, s46
	s_xor_b32 s44, s44, s17
	s_sub_i32 s44, s44, s17
	s_mul_i32 s17, s44, s19
	s_sub_i32 s9, s9, s17
	s_add_i32 s46, s9, s18

;     __host__ __device__ bool next(int i, Unit& u) const {
;         const long L = (long)i * G + c; if (L >= nwg) return false;
;         int wgid = (int)L; { const int q = nwg / NXCD, r = nwg % NXCD, xcd = wgid % NXCD, off = wgid / NXCD; wgid = (xcd < r ? xcd * (q + 1) : r * (q + 1) + (xcd - r) * q) + off; }
;         const int nig = WGM * nN, gid = wgid / nig, fm = gid * WGM, gsz = (nM - fm) < WGM ? (nM - fm) : WGM;
;         u.pm = fm + ((wgid % nig) % gsz); u.pn = (wgid % nig) / gsz; return true;
;     }
; template <class Epi, class Sched, bool ALIGN_EPI = false, bool SP2 = false>
; __device__ __forceinline__ void gemm_phase(PG8_LAS unsigned char* lds, const Gemm g, const Sched& S, const Epi& E, const int wave0) {
;     ...
;     if (!S.next(0, cur)) return;
.LBB0_2047:
	s_and_b64 vcc, exec, s[12:13]
	s_cbranch_vccz .LBB0_979
	s_min_u32 s2, s72, 0xe0
	s_cmp_ge_u32 s21, s2
	s_cselect_b32 s21, 0x7fffff, s21
	s_cmp_lt_i32 s21, s42
	v_mov_b32_e32 v0, v246
	s_cselect_b64 s[2:3], -1, 0
	s_cmp_ge_i32 s21, s42
	s_cbranch_scc1 .LBB0_2050
	s_lshl_b32 s7, s20, 3
	v_cvt_f32_u32_e32 v1, s7
	s_ashr_i32 s5, s21, 31
	s_lshr_b32 s5, s5, 29
	s_add_i32 s5, s21, s5
	v_rcp_iflag_f32_e32 v1, v1
	s_ashr_i32 s6, s5, 3
	s_and_b32 s5, s5, -8
	s_sub_i32 s5, s21, s5
	v_mul_f32_e32 v1, 0x4f7ffffe, v1
	v_cvt_u32_f32_e32 v1, v1
	s_lshr_b32 s4, s42, 3
	s_lshr_b32 s8, s5, 31
	s_or_b32 s4, s4, s8
	s_sub_i32 s8, 0, s7
	v_readfirstlane_b32 s9, v1
	s_mul_i32 s4, s5, s4
	s_mul_i32 s8, s8, s9
	s_add_i32 s4, s4, s6
	s_mul_hi_u32 s8, s9, s8
	s_abs_i32 s6, s4
	s_add_i32 s9, s9, s8
	s_mul_hi_u32 s8, s6, s9
	s_mul_i32 s9, s8, s7
	s_sub_i32 s6, s6, s9
	s_ashr_i32 s5, s4, 31
	s_add_i32 s9, s8, 1
	s_sub_i32 s10, s6, s7
	s_cmp_ge_u32 s6, s7
	s_cselect_b32 s8, s9, s8
	s_cselect_b32 s6, s10, s6
	s_add_i32 s9, s8, 1
	s_cmp_ge_u32 s6, s7
	s_cselect_b32 s6, s9, s8
	s_xor_b32 s6, s6, s5
	s_sub_i32 s5, s6, s5
	s_lshl_b32 s6, s5, 3
	s_sub_i32 s8, s35, s6
	s_min_i32 s8, s8, 8
	s_mul_i32 s5, s5, s7
	s_sext_i32_i16 s7, s8
	v_cvt_f32_i32_e32 v1, s7
	s_sub_i32 s9, s4, s5
	s_sext_i32_i16 s4, s9
	v_cvt_f32_i32_e32 v2, s4
	v_rcp_iflag_f32_e32 v3, v1
	s_xor_b32 s4, s4, s7
	s_ashr_i32 s4, s4, 30
	s_or_b32 s7, s4, 1
	v_mul_f32_e32 v3, v2, v3
	v_trunc_f32_e32 v3, v3
	v_fma_f32 v2, -v3, v1, v2
	v_cvt_i32_f32_e32 v3, v3
	v_cmp_ge_f32_e64 s[4:5], |v2|, |v1|
	s_and_b64 s[4:5], s[4:5], exec
	s_cselect_b32 s4, s7, 0
	v_readfirstlane_b32 s5, v3
	s_add_i32 s4, s5, s4
	s_sext_i32_i16 s54, s4
	s_mul_i32 s4, s4, s8
	s_sub_i32 s4, s9, s4
	s_sext_i32_i16 s4, s4
	s_add_i32 s8, s6, s4

; __device__ __forceinline__ int make_tid(int wave0) { int t = wave0 * 64 + (int)__builtin_amdgcn_mbcnt_hi(~0u, __builtin_amdgcn_mbcnt_lo(~0u, 0u)); asm volatile("" : "+v"(t)); return t; }
; #define PG8_STAGE(bufoff, gbase, voff) do { _Pragma("unroll") for (int _i = 0; _i < 2; ++_i) \
;         __builtin_amdgcn_global_load_lds((const unsigned*)((const char*)(gbase) + (voff)[_i]), (PG8_LAS unsigned*)(lds + (bufoff) + ldsw + _i * 8192), 16, 0, 0); } while (0)
; #define PG8_WAIT_V(n) asm volatile("s_waitcnt vmcnt(" #n ")" ::: "memory")
; #define PG8_BAR __builtin_amdgcn_s_barrier()
; template <class Epi, class Sched, bool ALIGN_EPI = false, bool SP2 = false>
; __device__ __forceinline__ void gemm_phase(PG8_LAS unsigned char* lds, const Gemm g, const Sched& S, const Epi& E, const int wave0) {
;     const int tid = make_tid(wave0), wid = wave0, lane = tid & 63, wr = wid >> 2, wc = wid & 3, fr = lane & 15, fq = lane >> 4;
;     const int K = g.K, nt = K / BK;
;     unsigned voffA[2], voffB[2];
; #pragma unroll
;     for (int i = 0; i < 2; ++i) { int R, C; stage_rc(tid * 16 + i * 8192, R, C); const int Rb = Epi::PERM ? ((R & ~31) + perm32(R & 31)) : R;
;         voffA[i] = (unsigned)(R * K + C) * 2u; voffB[i] = (unsigned)(Rb * K + C) * 2u; }
;     const size_t kstep = (size_t)(BK * 2);
;     const size_t hstep = (size_t)HALF * K * 2;
;     const size_t tstep = 2 * hstep;
;     const unsigned ldsw = (unsigned)wid * 1024u;
;     const int aoff = lds_byte(wr * 64 + fr, fq * 8), boff = lds_byte(wc * 32 + fr, fq * 8);
;     ...
;         PG8_STAGE(PG8_SB(0, 0), cB, voffB); PG8_STAGE(PG8_SB(0, 1), cB + hstep, voffB); PG8_STAGE(PG8_SA(0, 0), cA, voffA); PG8_STAGE(PG8_SA(0, 1), cA + hstep, voffA);
;         if (wr == 1) PG8_BAR;
;         PG8_WAIT_V(2); PG8_BAR;
;         PG8_STAGE(PG8_SB(1, 0), cB + kstep, voffB); PG8_STAGE(PG8_SA(1, 0), cA + kstep, voffA); PG8_STAGE(PG8_SB(1, 1), cB + hstep + kstep, voffB);
;         PG8_WAIT_V(6); PG8_BAR;
.LBB0_2053:
	v_and_b32_e32 v1, 15, v0
	v_readlane_b32 s4, v253, 9
	v_bfe_u32 v10, v0, 4, 2
	v_lshlrev_b32_e32 v11, 4, v10
	v_or_b32_e32 v221, s4, v1
	v_lshlrev_b32_e32 v12, 6, v221
	s_movk_i32 s4, 0x3c0
	v_lshlrev_b32_e32 v13, 2, v221
	v_mov_b32_e32 v217, v215
	v_and_or_b32 v12, v12, s4, v11
	v_and_b32_e32 v13, 32, v13
	v_readlane_b32 s4, v253, 10
	v_lshlrev_b32_e32 v0, 2, v0
	v_lshl_add_u64 v[2:3], s[12:13], 0, v[216:217]
	v_mov_b32_e32 v219, v215
	v_bitop3_b32 v12, v12, s4, v13 bitop3:0xde
	v_lshl_or_b32 v1, v1, 6, v11
	v_and_b32_e32 v0, 32, v0
	v_readlane_b32 s4, v254, 31
	v_lshl_add_u64 v[4:5], s[12:13], 0, v[218:219]
	s_add_i32 m0, s33, 0x18000
	v_bitop3_b32 v238, v1, s4, v0 bitop3:0xde
	v_lshl_add_u64 v[0:1], v[2:3], 0, s[78:79]
	v_lshl_add_u64 v[6:7], s[10:11], 0, v[216:217]
	s_waitcnt vmcnt(2)
	s_barrier
	global_load_lds_dwordx4 v[0:1], off
	v_lshl_add_u64 v[0:1], v[4:5], 0, s[78:79]
	s_add_i32 m0, s33, 0x1a000
	s_add_i32 s17, s33, 0x8000
	s_add_i32 s22, s33, 0xa000
	v_lshl_add_u64 v[8:9], s[10:11], 0, v[218:219]
	global_load_lds_dwordx4 v[0:1], off
	v_lshl_add_u64 v[0:1], v[6:7], 0, s[78:79]
	s_mov_b32 m0, s17
	s_add_u32 s4, s12, 0x8080
	global_load_lds_dwordx4 v[0:1], off
	v_lshl_add_u64 v[0:1], v[8:9], 0, s[78:79]
	s_mov_b32 m0, s22
	s_addc_u32 s5, s13, 0
	global_load_lds_dwordx4 v[0:1], off
	v_lshl_add_u64 v[0:1], s[4:5], 0, v[216:217]
	s_add_i32 m0, s33, 0x1c000
	s_lshl_b32 s20, s20, 3
	global_load_lds_dwordx4 v[0:1], off
	v_lshl_add_u64 v[0:1], s[4:5], 0, v[218:219]
	s_add_i32 m0, s33, 0x1e000
	s_sub_i32 s7, 0, s20
	global_load_lds_dwordx4 v[0:1], off
	v_cvt_f32_u32_e32 v0, s20
	s_waitcnt vmcnt(6)
	s_ashr_i32 s6, s21, 31
	s_lshr_b32 s23, s42, 3
	v_rcp_iflag_f32_e32 v0, v0
	v_lshlrev_b32_e32 v220, 2, v10
	v_cmp_eq_u32_e64 s[4:5], 0, v10
	s_mov_b32 s43, s81
	v_mul_f32_e32 v0, 0x4f7ffffe, v0
	v_cvt_u32_f32_e32 v0, v0
	v_add_u32_e32 v239, 0, v12
	s_barrier
	v_readfirstlane_b32 s9, v0
	s_mul_i32 s7, s7, s9
	s_mul_hi_u32 s7, s9, s7
	s_add_i32 s24, s9, s7
	s_min_u32 s45, s72, 0xe0
	s_add_u32 s44, s45, s21
	s_addc_u32 s45, 0, s6
	s_branch .LBB0_2056
.LBB0_2054:
	s_min_u32 s6, s72, 0xe0
	s_add_u32 s44, s44, s6
	s_addc_u32 s45, s45, 0
	s_mov_b64 s[6:7], 0
